# P1 row-sum butterfly: xor 1/2/4/8 hops via DPP instead of ds_bpermute round trips (bit-identical)
# speedup vs baseline: 1.0029x; 1.0029x over previous
.LBB0_111:
	v_add_co_u32_e32 v80, vcc, 0x1000, v116
	global_load_dwordx4 v[76:79], v[116:117], off nt
	global_load_dwordx4 v[72:75], v[116:117], off offset:1024 nt
	global_load_dwordx4 v[68:71], v[116:117], off offset:2048 nt
	global_load_dwordx4 v[64:67], v[116:117], off offset:3072 nt
	v_addc_co_u32_e32 v81, vcc, 0, v117, vcc
	v_add_co_u32_e32 v84, vcc, 0x2000, v116
	global_load_dwordx4 v[128:131], v[80:81], off offset:1024 nt
	global_load_dwordx4 v[132:135], v[80:81], off nt
	global_load_dwordx4 v[136:139], v[80:81], off offset:3072 nt
	global_load_dwordx4 v[140:143], v[80:81], off offset:2048 nt
	v_addc_co_u32_e32 v85, vcc, 0, v117, vcc
	global_load_dwordx4 v[80:83], v[84:85], off offset:2048 nt
	global_load_dwordx4 v[96:99], v[84:85], off nt
	global_load_dwordx4 v[88:91], v[84:85], off offset:1024 nt
	s_nop 0
	global_load_dwordx4 v[84:87], v[84:85], off offset:3072 nt
	v_add_co_u32_e32 v92, vcc, 0x3000, v116
	s_add_i32 s0, s6, 1
	s_nop 0
	v_addc_co_u32_e32 v93, vcc, 0, v117, vcc
	global_load_dwordx4 v[100:103], v[92:93], off offset:1024 nt
	global_load_dwordx4 v[108:111], v[92:93], off nt
	global_load_dwordx4 v[104:107], v[92:93], off offset:2048 nt
	s_nop 0
	global_load_dwordx4 v[92:95], v[92:93], off offset:3072 nt
	s_ashr_i32 s1, s0, 31
	s_lshl_b64 s[0:1], s[0:1], 12
	v_lshl_add_u64 v[118:119], v[112:113], 0, s[0:1]
	s_add_i32 s6, s6, 8
	v_lshl_add_u64 v[116:117], v[116:117], 0, s[10:11]
	s_cmp_lt_i32 s6, s14
	s_waitcnt vmcnt(15)
	v_mov_b32_e32 v150, v77
	s_waitcnt vmcnt(14)
	v_mov_b32_e32 v151, v73
	v_mov_b32_e32 v154, v79
	v_mov_b32_e32 v155, v75
	v_mov_b32_e32 v148, v76
	v_mov_b32_e32 v149, v72
	v_mov_b32_e32 v152, v78
	v_mov_b32_e32 v153, v74
	s_waitcnt vmcnt(13)
	v_pk_mul_f32 v[156:157], v[70:71], v[70:71]
	v_pk_mul_f32 v[158:159], v[68:69], v[68:69]
	v_pk_mul_f32 v[150:151], v[150:151], v[150:151]
	v_pk_mul_f32 v[154:155], v[154:155], v[154:155]
	s_waitcnt vmcnt(12)
	v_mul_f32_e32 v160, v65, v65
	v_mul_f32_e32 v162, v67, v67
	v_pk_mov_b32 v[164:165], v[158:159], v[156:157] op_sel:[1,0]
	v_mov_b32_e32 v159, v157
	v_pk_fma_f32 v[148:149], v[148:149], v[148:149], v[150:151]
	v_pk_fma_f32 v[150:151], v[152:153], v[152:153], v[154:155]
	v_pk_fma_f32 v[156:157], v[64:65], v[64:65], v[160:161] op_sel_hi:[1,1,0]
	v_pk_fma_f32 v[160:161], v[66:67], v[66:67], v[162:163] op_sel_hi:[1,1,0]
	v_pk_add_f32 v[152:153], v[164:165], v[158:159]
	s_waitcnt vmcnt(11)
	v_pk_mul_f32 v[154:155], v[130:131], v[130:131]
	v_pk_mul_f32 v[158:159], v[128:129], v[128:129]
	s_waitcnt vmcnt(8)
	v_mul_f32_e32 v162, v141, v141
	v_mul_f32_e32 v164, v143, v143
	v_pk_add_f32 v[148:149], v[148:149], v[150:151]
	v_mul_f32_e32 v145, v132, v132
	v_mul_f32_e32 v157, v134, v134
	v_mul_f32_e32 v161, v135, v135
	v_mul_f32_e32 v177, v133, v133
	v_mul_f32_e32 v179, v138, v138
	v_mul_f32_e32 v180, v139, v139
	v_pk_mov_b32 v[150:151], v[158:159], v[154:155] op_sel:[1,0]
	v_mov_b32_e32 v159, v155
	v_pk_add_f32 v[152:153], v[152:153], v[152:153] op_sel:[0,1] op_sel_hi:[1,0]
	v_pk_fma_f32 v[154:155], v[140:141], v[140:141], v[162:163] op_sel_hi:[1,1,0]
	v_pk_fma_f32 v[162:163], v[142:143], v[142:143], v[164:165] op_sel_hi:[1,1,0]
	s_waitcnt vmcnt(7)
	v_pk_mul_f32 v[164:165], v[82:83], v[82:83]
	v_pk_mul_f32 v[166:167], v[80:81], v[80:81]
	s_waitcnt vmcnt(6)
	v_mov_b32_e32 v170, v97
	s_waitcnt vmcnt(5)
	v_mov_b32_e32 v171, v89
	v_mov_b32_e32 v174, v99
	v_mov_b32_e32 v175, v91
	v_pk_add_f32 v[148:149], v[148:149], v[148:149] op_sel:[0,1] op_sel_hi:[1,0]
	v_mov_b32_e32 v168, v96
	v_mov_b32_e32 v169, v88
	v_mov_b32_e32 v172, v98
	v_mov_b32_e32 v173, v90
	v_pk_add_f32 v[156:157], v[156:157], v[160:161]
	v_pk_add_f32 v[150:151], v[150:151], v[158:159]
	v_mov_b32_e32 v153, v177
	v_mov_b32_e32 v155, v179
	v_mov_b32_e32 v163, v180
	v_pk_mov_b32 v[158:159], v[166:167], v[164:165] op_sel:[1,0]
	v_mov_b32_e32 v167, v165
	v_pk_mul_f32 v[160:161], v[170:171], v[170:171]
	v_pk_mul_f32 v[164:165], v[174:175], v[174:175]
	v_mov_b32_e32 v149, v145
	v_pk_add_f32 v[154:155], v[154:155], v[162:163]
	v_pk_fma_f32 v[160:161], v[168:169], v[168:169], v[160:161]
	v_pk_fma_f32 v[162:163], v[172:173], v[172:173], v[164:165]
	v_pk_add_f32 v[148:149], v[148:149], v[152:153]
	s_waitcnt vmcnt(4)
	v_mul_f32_e32 v176, v85, v85
	v_mul_f32_e32 v178, v87, v87
	v_pk_add_f32 v[158:159], v[158:159], v[166:167]
	v_pk_add_f32 v[152:153], v[160:161], v[162:163]
	v_pk_add_f32 v[148:149], v[148:149], v[156:157]
	v_mul_f32_e32 v181, v136, v136
	v_mul_f32_e32 v183, v137, v137
	v_pk_fma_f32 v[176:177], v[84:85], v[84:85], v[176:177] op_sel_hi:[1,1,0]
	v_pk_fma_f32 v[178:179], v[86:87], v[86:87], v[178:179] op_sel_hi:[1,1,0]
	s_waitcnt vmcnt(2)
	v_mul_f32_e32 v186, v109, v109
	v_mul_f32_e32 v187, v108, v108
	v_pk_add_f32 v[150:151], v[150:151], v[150:151] op_sel:[0,1] op_sel_hi:[1,0]
	v_pk_add_f32 v[158:159], v[158:159], v[158:159] op_sel:[0,1] op_sel_hi:[1,0]
	v_pk_add_f32 v[152:153], v[152:153], v[152:153] op_sel:[0,1] op_sel_hi:[1,0]
	v_pk_add_f32 v[148:149], v[148:149], v[148:149] op_sel:[0,1] op_sel_hi:[1,0]
	v_pk_mul_f32 v[170:171], v[102:103], v[102:103]
	v_pk_mul_f32 v[174:175], v[100:101], v[100:101]
	v_mul_f32_e32 v177, v110, v110
	v_mul_f32_e32 v179, v111, v111
	v_mov_b32_e32 v151, v183
	v_mov_b32_e32 v159, v186
	v_mov_b32_e32 v153, v187
	v_mov_b32_e32 v149, v181
	v_pk_mov_b32 v[164:165], v[174:175], v[170:171] op_sel:[1,0]
	v_mov_b32_e32 v175, v171
	v_pk_add_f32 v[160:161], v[176:177], v[178:179]
	v_pk_add_f32 v[152:153], v[152:153], v[158:159]
	v_pk_add_f32 v[148:149], v[148:149], v[150:151]
	s_waitcnt vmcnt(1)
	v_mul_f32_e32 v180, v105, v105
	v_mul_f32_e32 v182, v107, v107
	v_pk_add_f32 v[162:163], v[164:165], v[174:175]
	v_pk_add_f32 v[150:151], v[152:153], v[160:161]
	v_pk_add_f32 v[148:149], v[148:149], v[154:155]
	s_waitcnt vmcnt(0)
	v_mul_f32_e32 v184, v94, v94
	v_mul_f32_e32 v185, v95, v95
	v_mul_f32_e32 v188, v93, v93
	v_mul_f32_e32 v189, v92, v92
	v_pk_fma_f32 v[166:167], v[104:105], v[104:105], v[180:181] op_sel_hi:[1,1,0]
	v_pk_fma_f32 v[168:169], v[106:107], v[106:107], v[182:183] op_sel_hi:[1,1,0]
	v_pk_add_f32 v[162:163], v[162:163], v[162:163] op_sel:[0,1] op_sel_hi:[1,0]
	v_pk_add_f32 v[150:151], v[150:151], v[150:151] op_sel:[0,1] op_sel_hi:[1,0]
	v_add_f32_e32 v145, v148, v149
	v_mov_b32_e32 v167, v184
	v_mov_b32_e32 v169, v185
	v_mov_b32_e32 v163, v188
	v_mov_b32_e32 v151, v189
	v_pk_add_f32 v[156:157], v[166:167], v[168:169]
	v_pk_add_f32 v[148:149], v[150:151], v[162:163]
	s_nop 0
	v_pk_add_f32 v[148:149], v[148:149], v[156:157]
	v_add_f32_dpp v145, v145, v145 quad_perm:[1,0,3,2] row_mask:0xf bank_mask:0xf
	s_nop 0
	v_add_f32_e32 v148, v148, v149
	v_add_f32_dpp v145, v145, v145 quad_perm:[2,3,0,1] row_mask:0xf bank_mask:0xf
	s_nop 0
	v_add_f32_dpp v148, v148, v148 quad_perm:[1,0,3,2] row_mask:0xf bank_mask:0xf
	v_add_f32_dpp v145, v145, v145 row_half_mirror row_mask:0xf bank_mask:0xf
	s_nop 0
	v_add_f32_dpp v148, v148, v148 quad_perm:[2,3,0,1] row_mask:0xf bank_mask:0xf
	v_add_f32_dpp v145, v145, v145 row_mirror row_mask:0xf bank_mask:0xf
	s_nop 0
	v_add_f32_dpp v148, v148, v148 row_half_mirror row_mask:0xf bank_mask:0xf
	ds_bpermute_b32 v147, v124, v145
	s_nop 0
	v_add_f32_dpp v148, v148, v148 row_mirror row_mask:0xf bank_mask:0xf
	s_waitcnt lgkmcnt(0)
	v_add_f32_e32 v145, v145, v147
	ds_bpermute_b32 v147, v125, v145
	ds_bpermute_b32 v149, v124, v148
	s_waitcnt lgkmcnt(1)
	v_add_f32_e32 v145, v145, v147
	v_fmamk_f32 v145, v145, 0x3a000000, v126
	s_waitcnt lgkmcnt(0)
	v_add_f32_e32 v148, v148, v149
	ds_bpermute_b32 v149, v125, v148
	v_mul_f32_e32 v147, 0x4f800000, v145
	v_cmp_gt_f32_e32 vcc, s7, v145
	s_nop 1
	v_cndmask_b32_e32 v145, v145, v147, vcc
	s_waitcnt lgkmcnt(0)
	v_add_f32_e32 v147, v148, v149
	v_sqrt_f32_e32 v148, v145
	v_fmamk_f32 v147, v147, 0x3a000000, v126
	v_mul_f32_e32 v149, 0x4f800000, v147
	v_cmp_gt_f32_e64 s[0:1], s7, v147
	v_add_u32_e32 v150, -1, v148
	v_add_u32_e32 v151, 1, v148
	v_cndmask_b32_e64 v147, v147, v149, s[0:1]
	v_sqrt_f32_e32 v149, v147
	v_fma_f32 v152, -v150, v148, v145
	v_fma_f32 v153, -v151, v148, v145
	v_cmp_ge_f32_e64 s[4:5], 0, v152
	s_nop 1
	v_cndmask_b32_e64 v148, v148, v150, s[4:5]
	v_cmp_lt_f32_e64 s[4:5], 0, v153
	v_add_u32_e32 v150, -1, v149
	v_fma_f32 v153, -v150, v149, v147
	v_cndmask_b32_e64 v148, v148, v151, s[4:5]
	v_add_u32_e32 v151, 1, v149
	v_mul_f32_e32 v152, 0x37800000, v148
	v_fma_f32 v154, -v151, v149, v147
	v_cndmask_b32_e32 v148, v148, v152, vcc
	v_cmp_ge_f32_e32 vcc, 0, v153
	v_cmp_class_f32_e64 s[4:5], v145, v127
	s_nop 0
	v_cndmask_b32_e32 v149, v149, v150, vcc
	v_cmp_lt_f32_e32 vcc, 0, v154
	v_cndmask_b32_e64 v145, v148, v145, s[4:5]
	s_nop 0
	v_cndmask_b32_e32 v148, v149, v151, vcc
	v_div_scale_f32 v149, s[4:5], v145, v145, 1.0
	v_mul_f32_e32 v151, 0x37800000, v148
	v_rcp_f32_e32 v152, v149
	v_cndmask_b32_e64 v148, v148, v151, s[0:1]
	v_cmp_class_f32_e64 s[0:1], v147, v127
	v_div_scale_f32 v150, vcc, 1.0, v145, 1.0
	s_nop 0
	v_cndmask_b32_e64 v147, v148, v147, s[0:1]
	v_div_scale_f32 v151, s[0:1], v147, v147, 1.0
	v_rcp_f32_e32 v154, v151
	v_fma_f32 v148, -v149, v152, 1.0
	v_fmac_f32_e32 v152, v148, v152
	v_mul_f32_e32 v148, v150, v152
	v_fma_f32 v155, -v149, v148, v150
	v_fma_f32 v156, -v151, v154, 1.0
	v_div_scale_f32 v153, s[0:1], 1.0, v147, 1.0
	v_fmac_f32_e32 v148, v155, v152
	v_fmac_f32_e32 v154, v156, v154
	v_fma_f32 v149, -v149, v148, v150
	v_mul_f32_e32 v150, v153, v154
	v_div_fmas_f32 v148, v149, v152, v148
	v_fma_f32 v149, -v151, v150, v153
	v_div_fixup_f32 v148, v148, v145, 1.0
	v_fmac_f32_e32 v150, v149, v154
	v_pk_mul_f32 v[76:77], v[76:77], v[148:149] op_sel_hi:[1,0]
	v_pk_mul_f32 v[78:79], v[78:79], v[148:149] op_sel_hi:[1,0]
	v_pk_mul_f32 v[68:69], v[68:69], v[148:149] op_sel_hi:[1,0]
	v_pk_mul_f32 v[70:71], v[70:71], v[148:149] op_sel_hi:[1,0]
	v_pk_mul_f32 v[64:65], v[64:65], v[148:149] op_sel_hi:[1,0]
	v_pk_mul_f32 v[66:67], v[66:67], v[148:149] op_sel_hi:[1,0]
	v_pk_mul_f32 v[132:133], v[132:133], v[148:149] op_sel_hi:[1,0]
	v_pk_mul_f32 v[134:135], v[134:135], v[148:149] op_sel_hi:[1,0]
	v_pk_mul_f32 v[128:129], v[128:129], v[148:149] op_sel_hi:[1,0]
	v_fma_f32 v145, -v151, v150, v153
	s_mov_b64 vcc, s[0:1]
	v_pk_mul_f32 v[72:73], v[72:73], v[148:149] op_sel_hi:[1,0]
	v_pk_mul_f32 v[74:75], v[74:75], v[148:149] op_sel_hi:[1,0]
	v_pk_mul_f32 v[130:131], v[130:131], v[148:149] op_sel_hi:[1,0]
	v_pk_mul_f32 v[140:141], v[140:141], v[148:149] op_sel_hi:[1,0]
	v_pk_mul_f32 v[142:143], v[142:143], v[148:149] op_sel_hi:[1,0]
	v_pk_mul_f32 v[136:137], v[136:137], v[148:149] op_sel_hi:[1,0]
	v_pk_mul_f32 v[138:139], v[138:139], v[148:149] op_sel_hi:[1,0]
	v_div_fmas_f32 v145, v145, v154, v150
	v_pk_fma_f32 v[78:79], v[2:3], v[78:79], v[10:11]
	v_pk_fma_f32 v[76:77], v[0:1], v[76:77], v[8:9]
	v_pk_fma_f32 v[70:71], v[18:19], v[70:71], v[26:27]
	v_pk_fma_f32 v[68:69], v[16:17], v[68:69], v[24:25]
	v_pk_fma_f32 v[66:67], v[66:67], v[22:23], v[30:31]
	v_pk_fma_f32 v[64:65], v[64:65], v[20:21], v[28:29]
	v_pk_fma_f32 v[134:135], v[134:135], v[34:35], v[42:43]
	v_pk_fma_f32 v[132:133], v[132:133], v[32:33], v[40:41]
	v_pk_fma_f32 v[128:129], v[128:129], v[36:37], v[44:45]
	v_pk_fma_f32 v[74:75], v[6:7], v[74:75], v[14:15]
	v_pk_fma_f32 v[72:73], v[4:5], v[72:73], v[12:13]
	v_pk_fma_f32 v[130:131], v[130:131], v[38:39], v[46:47]
	v_pk_fma_f32 v[142:143], v[142:143], v[50:51], v[58:59]
	v_pk_fma_f32 v[140:141], v[140:141], v[48:49], v[56:57]
	v_pk_fma_f32 v[138:139], v[138:139], v[54:55], v[62:63]
	v_pk_fma_f32 v[136:137], v[136:137], v[52:53], v[60:61]
	v_cvt_pk_bf16_f32 v76, v76, v77
	v_cvt_pk_bf16_f32 v77, v78, v79
	v_cvt_pk_bf16_f32 v68, v68, v69
	v_cvt_pk_bf16_f32 v69, v70, v71
	v_cvt_pk_bf16_f32 v64, v64, v65
	v_cvt_pk_bf16_f32 v65, v66, v67
	v_cvt_pk_bf16_f32 v66, v132, v133
	v_cvt_pk_bf16_f32 v67, v134, v135
	v_cvt_pk_bf16_f32 v70, v128, v129
	v_div_fixup_f32 v128, v145, v147, 1.0
	v_cvt_pk_bf16_f32 v72, v72, v73
	v_cvt_pk_bf16_f32 v73, v74, v75
	v_cvt_pk_bf16_f32 v71, v130, v131
	v_cvt_pk_bf16_f32 v74, v140, v141
	v_cvt_pk_bf16_f32 v75, v142, v143
	v_cvt_pk_bf16_f32 v78, v136, v137
	v_cvt_pk_bf16_f32 v79, v138, v139
	global_store_dwordx2 v[114:115], v[76:77], off
	global_store_dwordx2 v[114:115], v[72:73], off offset:512
	global_store_dwordx2 v[114:115], v[68:69], off offset:1024
	global_store_dwordx2 v[114:115], v[64:65], off offset:1536
	global_store_dwordx2 v[114:115], v[66:67], off offset:2048
	global_store_dwordx2 v[114:115], v[70:71], off offset:2560
	global_store_dwordx2 v[114:115], v[74:75], off offset:3072
	global_store_dwordx2 v[114:115], v[78:79], off offset:3584
	v_pk_mul_f32 v[64:65], v[96:97], v[128:129] op_sel_hi:[1,0]
	v_pk_mul_f32 v[66:67], v[98:99], v[128:129] op_sel_hi:[1,0]
	v_pk_mul_f32 v[68:69], v[88:89], v[128:129] op_sel_hi:[1,0]
	v_pk_mul_f32 v[70:71], v[90:91], v[128:129] op_sel_hi:[1,0]
	v_pk_mul_f32 v[72:73], v[80:81], v[128:129] op_sel_hi:[1,0]
	v_pk_mul_f32 v[74:75], v[82:83], v[128:129] op_sel_hi:[1,0]
	v_pk_mul_f32 v[76:77], v[84:85], v[128:129] op_sel_hi:[1,0]
	v_pk_mul_f32 v[78:79], v[86:87], v[128:129] op_sel_hi:[1,0]
	v_pk_mul_f32 v[80:81], v[108:109], v[128:129] op_sel_hi:[1,0]
	v_pk_mul_f32 v[82:83], v[110:111], v[128:129] op_sel_hi:[1,0]
	v_pk_mul_f32 v[84:85], v[100:101], v[128:129] op_sel_hi:[1,0]
	v_pk_mul_f32 v[86:87], v[102:103], v[128:129] op_sel_hi:[1,0]
	v_pk_mul_f32 v[88:89], v[104:105], v[128:129] op_sel_hi:[1,0]
	v_pk_mul_f32 v[90:91], v[106:107], v[128:129] op_sel_hi:[1,0]
	v_pk_mul_f32 v[92:93], v[92:93], v[128:129] op_sel_hi:[1,0]
	v_pk_mul_f32 v[94:95], v[94:95], v[128:129] op_sel_hi:[1,0]
	v_pk_fma_f32 v[66:67], v[2:3], v[66:67], v[10:11]
	v_pk_fma_f32 v[64:65], v[0:1], v[64:65], v[8:9]
	v_lshl_add_u64 v[114:115], v[114:115], 0, s[8:9]
	v_pk_fma_f32 v[70:71], v[6:7], v[70:71], v[14:15]
	v_pk_fma_f32 v[68:69], v[4:5], v[68:69], v[12:13]
	v_pk_fma_f32 v[74:75], v[18:19], v[74:75], v[26:27]
	v_pk_fma_f32 v[72:73], v[16:17], v[72:73], v[24:25]
	v_pk_fma_f32 v[78:79], v[22:23], v[78:79], v[30:31]
	v_pk_fma_f32 v[76:77], v[20:21], v[76:77], v[28:29]
	v_pk_fma_f32 v[82:83], v[34:35], v[82:83], v[42:43]
	v_pk_fma_f32 v[80:81], v[32:33], v[80:81], v[40:41]
	v_pk_fma_f32 v[86:87], v[38:39], v[86:87], v[46:47]
	v_pk_fma_f32 v[84:85], v[36:37], v[84:85], v[44:45]
	v_pk_fma_f32 v[90:91], v[50:51], v[90:91], v[58:59]
	v_pk_fma_f32 v[88:89], v[48:49], v[88:89], v[56:57]
	v_pk_fma_f32 v[94:95], v[54:55], v[94:95], v[62:63]
	v_pk_fma_f32 v[92:93], v[52:53], v[92:93], v[60:61]
	v_cvt_pk_bf16_f32 v64, v64, v65
	v_cvt_pk_bf16_f32 v65, v66, v67
	v_cvt_pk_bf16_f32 v66, v68, v69
	v_cvt_pk_bf16_f32 v67, v70, v71
	v_cvt_pk_bf16_f32 v68, v72, v73
	v_cvt_pk_bf16_f32 v69, v74, v75
	v_cvt_pk_bf16_f32 v70, v76, v77
	v_cvt_pk_bf16_f32 v71, v78, v79
	v_cvt_pk_bf16_f32 v72, v80, v81
	v_cvt_pk_bf16_f32 v73, v82, v83
	v_cvt_pk_bf16_f32 v74, v84, v85
	v_cvt_pk_bf16_f32 v75, v86, v87
	v_cvt_pk_bf16_f32 v76, v88, v89
	v_cvt_pk_bf16_f32 v77, v90, v91
	v_cvt_pk_bf16_f32 v78, v92, v93
	v_cvt_pk_bf16_f32 v79, v94, v95
	global_store_dwordx2 v[118:119], v[64:65], off
	global_store_dwordx2 v[118:119], v[66:67], off offset:512
	global_store_dwordx2 v[118:119], v[68:69], off offset:1024
	global_store_dwordx2 v[118:119], v[70:71], off offset:1536
	global_store_dwordx2 v[118:119], v[72:73], off offset:2048
	global_store_dwordx2 v[118:119], v[74:75], off offset:2560
	global_store_dwordx2 v[118:119], v[76:77], off offset:3072
	global_store_dwordx2 v[118:119], v[78:79], off offset:3584
	s_cbranch_scc1 .LBB0_111
